# de-serialized latency-bound loops: P1 adaLN table (35 loads in flight per index instead of 5 dependent round trips) and P4 GLA scan (16 chunks of loads in flight instead of one per round trip)
# speedup vs baseline: 1.0332x; 1.0096x over previous
; __device__ __forceinline__ void p1_rows(const Params& P, LAS unsigned char* lds, int G) {
;     ...
;     for (int idx = tid; idx < 2 * DM; idx += NTHREADS) { const int b = idx >> 11, col = idx & (DM - 1);
;         float sh = P.b_ada[col], sc = P.b_ada[DM + col];
;         for (int ks = 0; ks < KS_ADA; ++ks) { sh += adap[(size_t)(ks * 2 + b) * NADA + col]; sc += adap[(size_t)(ks * 2 + b) * NADA + DM + col]; }
;         TA[idx] = P.g_pre_mix[col] * (1.0f + sc); TC[idx] = sh; }
.LBB0_158:
	v_and_b32_e32 v2, 0x7ff, v9
	v_ashrrev_i32_e32 v6, 11, v9
	v_lshlrev_b32_e32 v0, 2, v2
	v_mul_i32_i24_e32 v6, 0xc000, v6
	s_add_u32 s8, s68, 0x2000
	s_addc_u32 s9, s69, 0
	v_lshl_or_b32 v6, v2, 2, v6
	global_load_dword v4, v0, s[68:69]
	global_load_dword v5, v0, s[8:9]
	global_load_dword v44, v0, s[70:71]
	s_add_u32 s8, s58, 0x0
	s_addc_u32 s9, s59, 0
	global_load_dword v12, v6, s[8:9]
	s_add_u32 s8, s58, 0x2000
	s_addc_u32 s9, s59, 0
	global_load_dword v13, v6, s[8:9]
	s_add_u32 s8, s58, 0x18000
	s_addc_u32 s9, s59, 0
	global_load_dword v14, v6, s[8:9]
	s_add_u32 s8, s58, 0x1a000
	s_addc_u32 s9, s59, 0
	global_load_dword v15, v6, s[8:9]
	s_add_u32 s8, s58, 0x30000
	s_addc_u32 s9, s59, 0
	global_load_dword v16, v6, s[8:9]
	s_add_u32 s8, s58, 0x32000
	s_addc_u32 s9, s59, 0
	global_load_dword v17, v6, s[8:9]
	s_add_u32 s8, s58, 0x48000
	s_addc_u32 s9, s59, 0
	global_load_dword v18, v6, s[8:9]
	s_add_u32 s8, s58, 0x4a000
	s_addc_u32 s9, s59, 0
	global_load_dword v19, v6, s[8:9]
	s_add_u32 s8, s58, 0x60000
	s_addc_u32 s9, s59, 0
	global_load_dword v20, v6, s[8:9]
	s_add_u32 s8, s58, 0x62000
	s_addc_u32 s9, s59, 0
	global_load_dword v21, v6, s[8:9]
	s_add_u32 s8, s58, 0x78000
	s_addc_u32 s9, s59, 0
	global_load_dword v22, v6, s[8:9]
	s_add_u32 s8, s58, 0x7a000
	s_addc_u32 s9, s59, 0
	global_load_dword v23, v6, s[8:9]
	s_add_u32 s8, s58, 0x90000
	s_addc_u32 s9, s59, 0
	global_load_dword v24, v6, s[8:9]
	s_add_u32 s8, s58, 0x92000
	s_addc_u32 s9, s59, 0
	global_load_dword v25, v6, s[8:9]
	s_add_u32 s8, s58, 0xa8000
	s_addc_u32 s9, s59, 0
	global_load_dword v26, v6, s[8:9]
	s_add_u32 s8, s58, 0xaa000
	s_addc_u32 s9, s59, 0
	global_load_dword v27, v6, s[8:9]
	s_add_u32 s8, s58, 0xc0000
	s_addc_u32 s9, s59, 0
	global_load_dword v28, v6, s[8:9]
	s_add_u32 s8, s58, 0xc2000
	s_addc_u32 s9, s59, 0
	global_load_dword v29, v6, s[8:9]
	s_add_u32 s8, s58, 0xd8000
	s_addc_u32 s9, s59, 0
	global_load_dword v30, v6, s[8:9]
	s_add_u32 s8, s58, 0xda000
	s_addc_u32 s9, s59, 0
	global_load_dword v31, v6, s[8:9]
	s_add_u32 s8, s58, 0xf0000
	s_addc_u32 s9, s59, 0
	global_load_dword v32, v6, s[8:9]
	s_add_u32 s8, s58, 0xf2000
	s_addc_u32 s9, s59, 0
	global_load_dword v33, v6, s[8:9]
	s_add_u32 s8, s58, 0x108000
	s_addc_u32 s9, s59, 0
	global_load_dword v34, v6, s[8:9]
	s_add_u32 s8, s58, 0x10a000
	s_addc_u32 s9, s59, 0
	global_load_dword v35, v6, s[8:9]
	s_add_u32 s8, s58, 0x120000
	s_addc_u32 s9, s59, 0
	global_load_dword v36, v6, s[8:9]
	s_add_u32 s8, s58, 0x122000
	s_addc_u32 s9, s59, 0
	global_load_dword v37, v6, s[8:9]
	s_add_u32 s8, s58, 0x138000
	s_addc_u32 s9, s59, 0
	global_load_dword v38, v6, s[8:9]
	s_add_u32 s8, s58, 0x13a000
	s_addc_u32 s9, s59, 0
	global_load_dword v39, v6, s[8:9]
	s_add_u32 s8, s58, 0x150000
	s_addc_u32 s9, s59, 0
	global_load_dword v40, v6, s[8:9]
	s_add_u32 s8, s58, 0x152000
	s_addc_u32 s9, s59, 0
	global_load_dword v41, v6, s[8:9]
	s_add_u32 s8, s58, 0x168000
	s_addc_u32 s9, s59, 0
	global_load_dword v42, v6, s[8:9]
	s_add_u32 s8, s58, 0x16a000
	s_addc_u32 s9, s59, 0
	global_load_dword v43, v6, s[8:9]
	v_add_u32_e32 v6, 0x200, v9
	v_cmp_lt_i32_e32 vcc, s10, v9
	v_lshl_add_u32 v7, v9, 2, 0
	v_add_u16_e32 v3, 0x200, v3
	s_or_b64 s[6:7], vcc, s[6:7]
	v_mov_b32_e32 v9, v6
	s_waitcnt vmcnt(30)
	v_pk_add_f32 v[4:5], v[4:5], v[12:13]
	s_waitcnt vmcnt(28)
	v_pk_add_f32 v[4:5], v[4:5], v[14:15]
	s_waitcnt vmcnt(26)
	v_pk_add_f32 v[4:5], v[4:5], v[16:17]
	s_waitcnt vmcnt(24)
	v_pk_add_f32 v[4:5], v[4:5], v[18:19]
	s_waitcnt vmcnt(22)
	v_pk_add_f32 v[4:5], v[4:5], v[20:21]
	s_waitcnt vmcnt(20)
	v_pk_add_f32 v[4:5], v[4:5], v[22:23]
	s_waitcnt vmcnt(18)
	v_pk_add_f32 v[4:5], v[4:5], v[24:25]
	s_waitcnt vmcnt(16)
	v_pk_add_f32 v[4:5], v[4:5], v[26:27]
	s_waitcnt vmcnt(14)
	v_pk_add_f32 v[4:5], v[4:5], v[28:29]
	s_waitcnt vmcnt(12)
	v_pk_add_f32 v[4:5], v[4:5], v[30:31]
	s_waitcnt vmcnt(10)
	v_pk_add_f32 v[4:5], v[4:5], v[32:33]
	s_waitcnt vmcnt(8)
	v_pk_add_f32 v[4:5], v[4:5], v[34:35]
	s_waitcnt vmcnt(6)
	v_pk_add_f32 v[4:5], v[4:5], v[36:37]
	s_waitcnt vmcnt(4)
	v_pk_add_f32 v[4:5], v[4:5], v[38:39]
	s_waitcnt vmcnt(2)
	v_pk_add_f32 v[4:5], v[4:5], v[40:41]
	s_waitcnt vmcnt(0)
	v_pk_add_f32 v[4:5], v[4:5], v[42:43]
	v_add_f32_e32 v2, 1.0, v5
	s_nop 0
	v_mul_f32_e32 v0, v2, v44
	ds_write2st64_b32 v7, v0, v4 offset1:64
	s_andn2_b64 exec, exec, s[6:7]
	s_cbranch_execnz .LBB0_158

; __device__ __forceinline__ unsigned pk2(float lo, float hi) { return pg8::cvtpk(lo, hi); }
; __device__ __forceinline__ void gla_scan(const Params& P, int G) {
;     ...
;     if (threadIdx.x < 256) for (int gid = blockIdx.x * 256 + threadIdx.x; gid < 8 * 8192; gid += G * 256) {
;         const int bh = gid >> 13, e4 = gid & 8191, d = (4 * e4) & 127;
;         f32x4 st = {0.f, 0.f, 0.f, 0.f};
; #pragma unroll 16
;         for (int n = 0; n < 128; ++n) { const size_t unit = (size_t)bh * 128 + n;
;             const u32x2 w = *(const u32x2*)(DS + unit * 32768 + 4 * e4); const f32x4 dd = *(const f32x4*)(decay_g + unit * 128 + d);
;             u32x2 o; o.x = pk2(st[0], st[1]); o.y = pk2(st[2], st[3]); *(u32x2*)(ST + unit * 32768 + 4 * e4) = o;
;             f32x4 in; in[0] = __uint_as_float(w.x << 16); in[1] = __uint_as_float(w.x & 0xffff0000u); in[2] = __uint_as_float(w.y << 16); in[3] = __uint_as_float(w.y & 0xffff0000u);
;             st = dd * st + in; }
.LBB0_485:
	s_add_u32 s26, s58, 0x6800000
	s_addc_u32 s27, s59, 0
	global_load_dwordx2 v[26:27], v2, s[26:27]
	s_add_u32 s26, s58, 0x200000
	s_addc_u32 s27, s59, 0
	global_load_dwordx4 v[58:61], v0, s[26:27]
	s_add_u32 s26, s58, 0x6810000
	s_addc_u32 s27, s59, 0
	global_load_dwordx2 v[28:29], v2, s[26:27]
	s_add_u32 s26, s58, 0x200200
	s_addc_u32 s27, s59, 0
	global_load_dwordx4 v[62:65], v0, s[26:27]
	s_add_u32 s26, s58, 0x6820000
	s_addc_u32 s27, s59, 0
	global_load_dwordx2 v[30:31], v2, s[26:27]
	s_add_u32 s26, s58, 0x200400
	s_addc_u32 s27, s59, 0
	global_load_dwordx4 v[66:69], v0, s[26:27]
	s_add_u32 s26, s58, 0x6830000
	s_addc_u32 s27, s59, 0
	global_load_dwordx2 v[32:33], v2, s[26:27]
	s_add_u32 s26, s58, 0x200600
	s_addc_u32 s27, s59, 0
	global_load_dwordx4 v[70:73], v0, s[26:27]
	s_add_u32 s26, s58, 0x6840000
	s_addc_u32 s27, s59, 0
	global_load_dwordx2 v[34:35], v2, s[26:27]
	s_add_u32 s26, s58, 0x200800
	s_addc_u32 s27, s59, 0
	global_load_dwordx4 v[74:77], v0, s[26:27]
	s_add_u32 s26, s58, 0x6850000
	s_addc_u32 s27, s59, 0
	global_load_dwordx2 v[36:37], v2, s[26:27]
	s_add_u32 s26, s58, 0x200a00
	s_addc_u32 s27, s59, 0
	global_load_dwordx4 v[78:81], v0, s[26:27]
	s_add_u32 s26, s58, 0x6860000
	s_addc_u32 s27, s59, 0
	global_load_dwordx2 v[38:39], v2, s[26:27]
	s_add_u32 s26, s58, 0x200c00
	s_addc_u32 s27, s59, 0
	global_load_dwordx4 v[82:85], v0, s[26:27]
	s_add_u32 s26, s58, 0x6870000
	s_addc_u32 s27, s59, 0
	global_load_dwordx2 v[40:41], v2, s[26:27]
	s_add_u32 s26, s58, 0x200e00
	s_addc_u32 s27, s59, 0
	global_load_dwordx4 v[86:89], v0, s[26:27]
	s_add_u32 s26, s58, 0x6880000
	s_addc_u32 s27, s59, 0
	global_load_dwordx2 v[42:43], v2, s[26:27]
	s_add_u32 s26, s58, 0x201000
	s_addc_u32 s27, s59, 0
	global_load_dwordx4 v[90:93], v0, s[26:27]
	s_add_u32 s26, s58, 0x6890000
	s_addc_u32 s27, s59, 0
	global_load_dwordx2 v[44:45], v2, s[26:27]
	s_add_u32 s26, s58, 0x201200
	s_addc_u32 s27, s59, 0
	global_load_dwordx4 v[94:97], v0, s[26:27]
	s_add_u32 s26, s58, 0x68a0000
	s_addc_u32 s27, s59, 0
	global_load_dwordx2 v[46:47], v2, s[26:27]
	s_add_u32 s26, s58, 0x201400
	s_addc_u32 s27, s59, 0
	global_load_dwordx4 v[98:101], v0, s[26:27]
	s_add_u32 s26, s58, 0x68b0000
	s_addc_u32 s27, s59, 0
	global_load_dwordx2 v[48:49], v2, s[26:27]
	s_add_u32 s26, s58, 0x201600
	s_addc_u32 s27, s59, 0
	global_load_dwordx4 v[102:105], v0, s[26:27]
	s_add_u32 s26, s58, 0x68c0000
	s_addc_u32 s27, s59, 0
	global_load_dwordx2 v[50:51], v2, s[26:27]
	s_add_u32 s26, s58, 0x201800
	s_addc_u32 s27, s59, 0
	global_load_dwordx4 v[106:109], v0, s[26:27]
	s_add_u32 s26, s58, 0x68d0000
	s_addc_u32 s27, s59, 0
	global_load_dwordx2 v[52:53], v2, s[26:27]
	s_add_u32 s26, s58, 0x201a00
	s_addc_u32 s27, s59, 0
	global_load_dwordx4 v[110:113], v0, s[26:27]
	s_add_u32 s26, s58, 0x68e0000
	s_addc_u32 s27, s59, 0
	global_load_dwordx2 v[54:55], v2, s[26:27]
	s_add_u32 s26, s58, 0x201c00
	s_addc_u32 s27, s59, 0
	global_load_dwordx4 v[114:117], v0, s[26:27]
	s_add_u32 s26, s58, 0x68f0000
	s_addc_u32 s27, s59, 0
	global_load_dwordx2 v[56:57], v2, s[26:27]
	s_add_u32 s26, s58, 0x201e00
	s_addc_u32 s27, s59, 0
	global_load_dwordx4 v[118:121], v0, s[26:27]
	v_cvt_pk_bf16_f32 v22, v10, v11
	v_cvt_pk_bf16_f32 v23, v12, v13
	s_add_u32 s26, s58, 0x14800000
	s_addc_u32 s27, s59, 0
	global_store_dwordx2 v2, v[22:23], s[26:27]
	s_waitcnt vmcnt(31)
	v_lshlrev_b32_e32 v16, 16, v26
	v_and_b32_e32 v17, 0xffff0000, v26
	v_lshlrev_b32_e32 v18, 16, v27
	v_and_b32_e32 v19, 0xffff0000, v27
	v_pk_fma_f32 v[10:11], v[10:11], v[58:59], v[16:17]
	v_pk_fma_f32 v[12:13], v[12:13], v[60:61], v[18:19]
	v_cvt_pk_bf16_f32 v22, v10, v11
	v_cvt_pk_bf16_f32 v23, v12, v13
	s_add_u32 s26, s58, 0x14810000
	s_addc_u32 s27, s59, 0
	global_store_dwordx2 v2, v[22:23], s[26:27]
	s_waitcnt vmcnt(30)
	v_lshlrev_b32_e32 v16, 16, v28
	v_and_b32_e32 v17, 0xffff0000, v28
	v_lshlrev_b32_e32 v18, 16, v29
	v_and_b32_e32 v19, 0xffff0000, v29
	v_pk_fma_f32 v[10:11], v[10:11], v[62:63], v[16:17]
	v_pk_fma_f32 v[12:13], v[12:13], v[64:65], v[18:19]
	v_cvt_pk_bf16_f32 v22, v10, v11
	v_cvt_pk_bf16_f32 v23, v12, v13
	s_add_u32 s26, s58, 0x14820000
	s_addc_u32 s27, s59, 0
	global_store_dwordx2 v2, v[22:23], s[26:27]
	s_waitcnt vmcnt(29)
	v_lshlrev_b32_e32 v16, 16, v30
	v_and_b32_e32 v17, 0xffff0000, v30
	v_lshlrev_b32_e32 v18, 16, v31
	v_and_b32_e32 v19, 0xffff0000, v31
	v_pk_fma_f32 v[10:11], v[10:11], v[66:67], v[16:17]
	v_pk_fma_f32 v[12:13], v[12:13], v[68:69], v[18:19]
	v_cvt_pk_bf16_f32 v22, v10, v11
	v_cvt_pk_bf16_f32 v23, v12, v13
	s_add_u32 s26, s58, 0x14830000
	s_addc_u32 s27, s59, 0
	global_store_dwordx2 v2, v[22:23], s[26:27]
	s_waitcnt vmcnt(28)
	v_lshlrev_b32_e32 v16, 16, v32
	v_and_b32_e32 v17, 0xffff0000, v32
	v_lshlrev_b32_e32 v18, 16, v33
	v_and_b32_e32 v19, 0xffff0000, v33
	v_pk_fma_f32 v[10:11], v[10:11], v[70:71], v[16:17]
	v_pk_fma_f32 v[12:13], v[12:13], v[72:73], v[18:19]
	v_cvt_pk_bf16_f32 v22, v10, v11
	v_cvt_pk_bf16_f32 v23, v12, v13
	s_add_u32 s26, s58, 0x14840000
	s_addc_u32 s27, s59, 0
	global_store_dwordx2 v2, v[22:23], s[26:27]
	s_waitcnt vmcnt(27)
; __device__ __forceinline__ unsigned pk2(float lo, float hi) { return pg8::cvtpk(lo, hi); }
; __device__ __forceinline__ void gla_scan(const Params& P, int G) {
;     ...
;     if (threadIdx.x < 256) for (int gid = blockIdx.x * 256 + threadIdx.x; gid < 8 * 8192; gid += G * 256) {
;         const int bh = gid >> 13, e4 = gid & 8191, d = (4 * e4) & 127;
;         f32x4 st = {0.f, 0.f, 0.f, 0.f};
; #pragma unroll 16
;         for (int n = 0; n < 128; ++n) { const size_t unit = (size_t)bh * 128 + n;
;             const u32x2 w = *(const u32x2*)(DS + unit * 32768 + 4 * e4); const f32x4 dd = *(const f32x4*)(decay_g + unit * 128 + d);
;             u32x2 o; o.x = pk2(st[0], st[1]); o.y = pk2(st[2], st[3]); *(u32x2*)(ST + unit * 32768 + 4 * e4) = o;
;             f32x4 in; in[0] = __uint_as_float(w.x << 16); in[1] = __uint_as_float(w.x & 0xffff0000u); in[2] = __uint_as_float(w.y << 16); in[3] = __uint_as_float(w.y & 0xffff0000u);
;             st = dd * st + in; }
	v_lshlrev_b32_e32 v16, 16, v34
	v_and_b32_e32 v17, 0xffff0000, v34
	v_lshlrev_b32_e32 v18, 16, v35
	v_and_b32_e32 v19, 0xffff0000, v35
	v_pk_fma_f32 v[10:11], v[10:11], v[74:75], v[16:17]
	v_pk_fma_f32 v[12:13], v[12:13], v[76:77], v[18:19]
	v_cvt_pk_bf16_f32 v22, v10, v11
	v_cvt_pk_bf16_f32 v23, v12, v13
	s_add_u32 s26, s58, 0x14850000
	s_addc_u32 s27, s59, 0
	global_store_dwordx2 v2, v[22:23], s[26:27]
	s_waitcnt vmcnt(26)
	v_lshlrev_b32_e32 v16, 16, v36
	v_and_b32_e32 v17, 0xffff0000, v36
	v_lshlrev_b32_e32 v18, 16, v37
	v_and_b32_e32 v19, 0xffff0000, v37
	v_pk_fma_f32 v[10:11], v[10:11], v[78:79], v[16:17]
	v_pk_fma_f32 v[12:13], v[12:13], v[80:81], v[18:19]
	v_cvt_pk_bf16_f32 v22, v10, v11
	v_cvt_pk_bf16_f32 v23, v12, v13
	s_add_u32 s26, s58, 0x14860000
	s_addc_u32 s27, s59, 0
	global_store_dwordx2 v2, v[22:23], s[26:27]
	s_waitcnt vmcnt(25)
	v_lshlrev_b32_e32 v16, 16, v38
	v_and_b32_e32 v17, 0xffff0000, v38
	v_lshlrev_b32_e32 v18, 16, v39
	v_and_b32_e32 v19, 0xffff0000, v39
	v_pk_fma_f32 v[10:11], v[10:11], v[82:83], v[16:17]
	v_pk_fma_f32 v[12:13], v[12:13], v[84:85], v[18:19]
	v_cvt_pk_bf16_f32 v22, v10, v11
	v_cvt_pk_bf16_f32 v23, v12, v13
	s_add_u32 s26, s58, 0x14870000
	s_addc_u32 s27, s59, 0
	global_store_dwordx2 v2, v[22:23], s[26:27]
	s_waitcnt vmcnt(24)
	v_lshlrev_b32_e32 v16, 16, v40
	v_and_b32_e32 v17, 0xffff0000, v40
	v_lshlrev_b32_e32 v18, 16, v41
	v_and_b32_e32 v19, 0xffff0000, v41
	v_pk_fma_f32 v[10:11], v[10:11], v[86:87], v[16:17]
	v_pk_fma_f32 v[12:13], v[12:13], v[88:89], v[18:19]
	v_cvt_pk_bf16_f32 v22, v10, v11
	v_cvt_pk_bf16_f32 v23, v12, v13
	s_add_u32 s26, s58, 0x14880000
	s_addc_u32 s27, s59, 0
	global_store_dwordx2 v2, v[22:23], s[26:27]
	s_waitcnt vmcnt(23)
	v_lshlrev_b32_e32 v16, 16, v42
	v_and_b32_e32 v17, 0xffff0000, v42
	v_lshlrev_b32_e32 v18, 16, v43
	v_and_b32_e32 v19, 0xffff0000, v43
	v_pk_fma_f32 v[10:11], v[10:11], v[90:91], v[16:17]
	v_pk_fma_f32 v[12:13], v[12:13], v[92:93], v[18:19]
	v_cvt_pk_bf16_f32 v22, v10, v11
	v_cvt_pk_bf16_f32 v23, v12, v13
	s_add_u32 s26, s58, 0x14890000
	s_addc_u32 s27, s59, 0
	global_store_dwordx2 v2, v[22:23], s[26:27]
	s_waitcnt vmcnt(22)
	v_lshlrev_b32_e32 v16, 16, v44
	v_and_b32_e32 v17, 0xffff0000, v44
	v_lshlrev_b32_e32 v18, 16, v45
	v_and_b32_e32 v19, 0xffff0000, v45
	v_pk_fma_f32 v[10:11], v[10:11], v[94:95], v[16:17]
	v_pk_fma_f32 v[12:13], v[12:13], v[96:97], v[18:19]
	v_cvt_pk_bf16_f32 v22, v10, v11
	v_cvt_pk_bf16_f32 v23, v12, v13
	s_add_u32 s26, s58, 0x148a0000
	s_addc_u32 s27, s59, 0
	global_store_dwordx2 v2, v[22:23], s[26:27]
	s_waitcnt vmcnt(21)
	v_lshlrev_b32_e32 v16, 16, v46
	v_and_b32_e32 v17, 0xffff0000, v46
	v_lshlrev_b32_e32 v18, 16, v47
	v_and_b32_e32 v19, 0xffff0000, v47
	v_pk_fma_f32 v[10:11], v[10:11], v[98:99], v[16:17]
	v_pk_fma_f32 v[12:13], v[12:13], v[100:101], v[18:19]
	v_cvt_pk_bf16_f32 v22, v10, v11
	v_cvt_pk_bf16_f32 v23, v12, v13
	s_add_u32 s26, s58, 0x148b0000
	s_addc_u32 s27, s59, 0
	global_store_dwordx2 v2, v[22:23], s[26:27]
	s_waitcnt vmcnt(20)
	v_lshlrev_b32_e32 v16, 16, v48
	v_and_b32_e32 v17, 0xffff0000, v48
	v_lshlrev_b32_e32 v18, 16, v49
	v_and_b32_e32 v19, 0xffff0000, v49
	v_pk_fma_f32 v[10:11], v[10:11], v[102:103], v[16:17]
	v_pk_fma_f32 v[12:13], v[12:13], v[104:105], v[18:19]
	v_cvt_pk_bf16_f32 v22, v10, v11
	v_cvt_pk_bf16_f32 v23, v12, v13
	s_add_u32 s26, s58, 0x148c0000
	s_addc_u32 s27, s59, 0
	global_store_dwordx2 v2, v[22:23], s[26:27]
	s_waitcnt vmcnt(19)
	v_lshlrev_b32_e32 v16, 16, v50
	v_and_b32_e32 v17, 0xffff0000, v50
	v_lshlrev_b32_e32 v18, 16, v51
	v_and_b32_e32 v19, 0xffff0000, v51
	v_pk_fma_f32 v[10:11], v[10:11], v[106:107], v[16:17]
	v_pk_fma_f32 v[12:13], v[12:13], v[108:109], v[18:19]
	v_cvt_pk_bf16_f32 v22, v10, v11
	v_cvt_pk_bf16_f32 v23, v12, v13
	s_add_u32 s26, s58, 0x148d0000
	s_addc_u32 s27, s59, 0
	global_store_dwordx2 v2, v[22:23], s[26:27]
	s_waitcnt vmcnt(18)
	v_lshlrev_b32_e32 v16, 16, v52
	v_and_b32_e32 v17, 0xffff0000, v52
	v_lshlrev_b32_e32 v18, 16, v53
	v_and_b32_e32 v19, 0xffff0000, v53
	v_pk_fma_f32 v[10:11], v[10:11], v[110:111], v[16:17]
	v_pk_fma_f32 v[12:13], v[12:13], v[112:113], v[18:19]
	v_cvt_pk_bf16_f32 v22, v10, v11
	v_cvt_pk_bf16_f32 v23, v12, v13
	s_add_u32 s26, s58, 0x148e0000
	s_addc_u32 s27, s59, 0
	global_store_dwordx2 v2, v[22:23], s[26:27]
	s_waitcnt vmcnt(17)
	v_lshlrev_b32_e32 v16, 16, v54
	v_and_b32_e32 v17, 0xffff0000, v54
	v_lshlrev_b32_e32 v18, 16, v55
	v_and_b32_e32 v19, 0xffff0000, v55
	v_pk_fma_f32 v[10:11], v[10:11], v[114:115], v[16:17]
	v_pk_fma_f32 v[12:13], v[12:13], v[116:117], v[18:19]
	v_cvt_pk_bf16_f32 v22, v10, v11
	v_cvt_pk_bf16_f32 v23, v12, v13
	s_add_u32 s26, s58, 0x148f0000
	s_addc_u32 s27, s59, 0
	global_store_dwordx2 v2, v[22:23], s[26:27]
	s_waitcnt vmcnt(16)
	v_lshlrev_b32_e32 v16, 16, v56
	v_and_b32_e32 v17, 0xffff0000, v56
	v_lshlrev_b32_e32 v18, 16, v57
	v_and_b32_e32 v19, 0xffff0000, v57
	v_pk_fma_f32 v[10:11], v[10:11], v[118:119], v[16:17]
	v_pk_fma_f32 v[12:13], v[12:13], v[120:121], v[18:19]
	s_mov_b64 s[26:27], 0x2000
	v_lshl_add_u64 v[0:1], v[0:1], 0, s[26:27]
	s_mov_b64 s[26:27], 0x100000
	v_lshl_add_u64 v[2:3], v[2:3], 0, s[26:27]
	s_add_i32 s23, s23, -16
	s_cmp_eq_u32 s23, 0
	s_cbranch_scc0 .LBB0_485
	v_add_u32_e32 v14, s3, v14
	s_mov_b32 s23, 0xffff
	v_cmp_lt_i32_e32 vcc, s23, v14
	s_or_b64 s[36:37], vcc, s[36:37]
	v_add_u32_e32 v15, s22, v15
	s_andn2_b64 exec, exec, s[36:37]
	s_cbranch_execnz .LBB0_484
